# v56 + indexer key-tile prefetch/rotation block moved into the mandatory MFMA-to-VALU gap after the last MFMA; layer-B block loop issues its K ds_reads before the window-mask arithmetic
# speedup vs baseline: 1.0054x; 1.0013x over previous
.LBB0_598:
	ds_read_b128 v[34:37], v128
	ds_read_b128 v[130:133], v128 offset:32
	ds_read_b128 v[134:137], v128 offset:64
	ds_read_b128 v[138:141], v128 offset:96
	v_lshl_add_u32 v254, 2, v127, -1
	v_cmp_lt_i32_e32 vcc, -1, v127
	v_add_u32_e32 v253, 0xffffff81, v127
	s_movk_i32 s11, 0x9f
	v_cndmask_b32_e32 v254, 0, v254, vcc
	v_cmp_gt_i32_e32 vcc, 31, v127
	v_lshlrev_b32_e64 v253, v253, -1
	s_nop 0
	v_cndmask_b32_e32 v254, -1, v254, vcc
	v_cmp_gt_i32_e32 vcc, s11, v127
	s_movk_i32 s11, 0x7f
	s_nop 0
	v_cndmask_b32_e32 v253, 0, v253, vcc
	v_cmp_lt_i32_e32 vcc, s11, v127
	s_nop 1
	v_cndmask_b32_e32 v253, -1, v253, vcc
	v_and_b32_e32 v142, v254, v253
	s_waitcnt lgkmcnt(3)
	v_mfma_f32_32x32x16_bf16 v[34:49], v[34:37], v[90:93], 0
	s_waitcnt lgkmcnt(2)
	v_mfma_f32_32x32x16_bf16 v[34:49], v[130:133], v[94:97], v[34:49]
	s_waitcnt lgkmcnt(1)
	v_mfma_f32_32x32x16_bf16 v[34:49], v[134:137], v[98:101], v[34:49]
	v_lshrrev_b32_e32 v134, v145, v142
	v_bfe_i32 v130, v134, 0, 1
	s_waitcnt lgkmcnt(0)
	v_mfma_f32_32x32x16_bf16 v[34:49], v[138:141], v[102:105], v[34:49]
	s_nop 11
	v_bitop3_b32 v130, v34, s70, v130 bitop3:0xe4
	v_bfe_i32 v34, v134, 1, 1
	v_bitop3_b32 v34, v35, s70, v34 bitop3:0xe4
	v_bfe_i32 v35, v134, 2, 1
	v_bitop3_b32 v131, v36, s70, v35 bitop3:0xe4
	v_bfe_i32 v35, v134, 3, 1
	v_max3_f32 v132, v130, s70, v34
	v_bitop3_b32 v35, v37, s70, v35 bitop3:0xe4
	v_bfe_i32 v37, v134, 8, 1
	v_max3_f32 v36, v132, v131, v35
	v_bitop3_b32 v132, v38, s70, v37 bitop3:0xe4
	v_bfe_i32 v37, v134, 9, 1
	v_bitop3_b32 v38, v39, s70, v37 bitop3:0xe4
	v_max3_f32 v37, v36, v132, v38
	v_bfe_i32 v36, v134, 10, 1
	v_bitop3_b32 v39, v40, s70, v36 bitop3:0xe4
	v_bfe_i32 v36, v134, 11, 1
	v_bitop3_b32 v36, v41, s70, v36 bitop3:0xe4
	v_max3_f32 v41, v37, v39, v36
	v_bfe_i32 v37, v134, 16, 1
	v_bitop3_b32 v37, v42, s70, v37 bitop3:0xe4
	v_bfe_i32 v42, v134, 18, 1
	v_bfe_i32 v40, v134, 17, 1
	v_bitop3_b32 v133, v44, s70, v42 bitop3:0xe4
	v_bfe_i32 v42, v134, 19, 1
	v_bitop3_b32 v40, v43, s70, v40 bitop3:0xe4
	v_bitop3_b32 v44, v45, s70, v42 bitop3:0xe4
	v_bfe_i32 v42, v134, 24, 1
	v_max3_f32 v41, v41, v37, v40
	v_bitop3_b32 v45, v46, s70, v42 bitop3:0xe4
	v_bfe_i32 v42, v134, 25, 1
	v_max3_f32 v41, v41, v133, v44
	v_bitop3_b32 v42, v47, s70, v42 bitop3:0xe4
	v_max3_f32 v46, v41, v45, v42
	v_bfe_i32 v41, v134, 26, 1
	v_bitop3_b32 v43, v48, s70, v41 bitop3:0xe4
	v_bfe_i32 v41, v134, 27, 1
	v_bitop3_b32 v41, v49, s70, v41 bitop3:0xe4
	v_max3_f32 v46, v46, v43, v41
	v_mov_b32_e32 v47, v46
	s_nop 1
	v_permlane32_swap_b32_e32 v47, v46
	v_max_f32_e32 v46, v46, v47
	v_add_f32_e32 v47, 0x41000000, v126
	v_cmp_gt_f32_e32 vcc, v46, v47
	s_cbranch_vccz .LBB0_597
	v_max_f32_e32 v46, v46, v46
	v_max_f32_e32 v47, v126, v126
	v_max_f32_e32 v47, v47, v46
	v_cmp_neq_f32_e32 vcc, s70, v47
	s_nop 1
	v_cndmask_b32_e32 v46, 0, v47, vcc
	v_sub_f32_e32 v46, v126, v46
	v_exp_f32_e32 v46, v46
	v_mov_b32_e32 v126, v47
	v_mul_f32_e32 v125, v125, v46
	v_pk_mul_f32 v[16:17], v[16:17], v[46:47] op_sel_hi:[1,0]
	v_pk_mul_f32 v[14:15], v[14:15], v[46:47] op_sel_hi:[1,0]
	v_pk_mul_f32 v[12:13], v[12:13], v[46:47] op_sel_hi:[1,0]
	v_pk_mul_f32 v[10:11], v[10:11], v[46:47] op_sel_hi:[1,0]
	v_pk_mul_f32 v[8:9], v[8:9], v[46:47] op_sel_hi:[1,0]
	v_pk_mul_f32 v[6:7], v[6:7], v[46:47] op_sel_hi:[1,0]
	v_pk_mul_f32 v[4:5], v[4:5], v[46:47] op_sel_hi:[1,0]
	v_pk_mul_f32 v[2:3], v[2:3], v[46:47] op_sel_hi:[1,0]
	v_pk_mul_f32 v[32:33], v[32:33], v[46:47] op_sel_hi:[1,0]
	v_pk_mul_f32 v[30:31], v[30:31], v[46:47] op_sel_hi:[1,0]
	v_pk_mul_f32 v[28:29], v[28:29], v[46:47] op_sel_hi:[1,0]
	v_pk_mul_f32 v[26:27], v[26:27], v[46:47] op_sel_hi:[1,0]
	v_pk_mul_f32 v[24:25], v[24:25], v[46:47] op_sel_hi:[1,0]
	v_pk_mul_f32 v[22:23], v[22:23], v[46:47] op_sel_hi:[1,0]
	v_pk_mul_f32 v[20:21], v[20:21], v[46:47] op_sel_hi:[1,0]
	v_pk_mul_f32 v[18:19], v[18:19], v[46:47] op_sel_hi:[1,0]
	s_branch .LBB0_597

.LBB0_649:
	s_barrier
	s_waitcnt vmcnt(2)
	ds_write_b128 v0, v[70:73]
	s_waitcnt lgkmcnt(0)
	s_barrier
	ds_read_b128 v[2:5], v126
	ds_read_b128 v[70:73], v126 offset:32
	s_waitcnt lgkmcnt(1)
	v_mfma_f32_32x32x16_bf16 v[18:33], v[34:37], v[2:5], 0
	ds_read_b128 v[2:5], v126 offset:4608
	ds_read_b128 v[128:131], v126 offset:4640
	s_add_i32 s6, s1, 4
	s_min_u32 s6, s6, s0
	s_lshl_b32 s52, s6, 6
	s_lshl_b64 s[6:7], s[52:53], 7
	s_add_i32 s1, s1, 1
	s_cmp_lg_u32 s0, s1
	s_waitcnt lgkmcnt(1)
	v_mfma_f32_32x32x16_bf16 v[2:17], v[34:37], v[2:5], 0
	v_mfma_f32_32x32x16_bf16 v[18:33], v[38:41], v[70:73], v[18:33]
	s_waitcnt lgkmcnt(0)
	v_mfma_f32_32x32x16_bf16 v[2:17], v[38:41], v[128:131], v[2:17]
	ds_read_b128 v[70:73], v126 offset:64
	ds_read_b128 v[128:131], v126 offset:96
	s_waitcnt lgkmcnt(1)
	v_mfma_f32_32x32x16_bf16 v[18:33], v[42:45], v[70:73], v[18:33]
	ds_read_b128 v[70:73], v126 offset:4672
	ds_read_b128 v[132:135], v126 offset:4704
	s_waitcnt lgkmcnt(1)
	v_mfma_f32_32x32x16_bf16 v[2:17], v[42:45], v[70:73], v[2:17]
	v_mfma_f32_32x32x16_bf16 v[18:33], v[46:49], v[128:131], v[18:33]
	s_waitcnt lgkmcnt(0)
	v_mfma_f32_32x32x16_bf16 v[2:17], v[46:49], v[132:135], v[2:17]
	s_waitcnt vmcnt(1)
	v_mov_b64_e32 v[72:73], v[68:69]
	v_mov_b64_e32 v[70:71], v[66:67]
	s_waitcnt vmcnt(0)
	v_mov_b64_e32 v[66:67], v[74:75]
	v_mov_b64_e32 v[68:69], v[76:77]
	v_lshl_add_u64 v[74:75], v[90:91], 0, s[6:7]
	global_load_dwordx4 v[74:77], v[74:75], off
	s_nop 3
	v_max_f32_e32 v18, 0, v18
	v_max_f32_e32 v26, 0, v26
	v_max_f32_e32 v2, 0, v2
	v_max_f32_e32 v10, 0, v10
	v_max_f32_e32 v19, 0, v19
	v_max_f32_e32 v27, 0, v27
	v_max_f32_e32 v3, 0, v3
	v_max_f32_e32 v11, 0, v11
	v_fma_f32 v18, v50, v18, 0
	v_fma_f32 v26, v58, v26, 0
	v_fma_f32 v2, v50, v2, 0
	v_fma_f32 v10, v58, v10, 0
	v_max_f32_e32 v20, 0, v20
	v_max_f32_e32 v28, 0, v28
	v_max_f32_e32 v4, 0, v4
	v_max_f32_e32 v12, 0, v12
	v_fmac_f32_e32 v18, v51, v19
	v_fmac_f32_e32 v26, v59, v27
	v_fmac_f32_e32 v2, v51, v3
	v_fmac_f32_e32 v10, v59, v11
	v_max_f32_e32 v21, 0, v21
	v_max_f32_e32 v29, 0, v29
	v_max_f32_e32 v5, 0, v5
	v_max_f32_e32 v13, 0, v13
	v_fmac_f32_e32 v18, v52, v20
	v_fmac_f32_e32 v26, v60, v28
	v_fmac_f32_e32 v2, v52, v4
	v_fmac_f32_e32 v10, v60, v12
	v_max_f32_e32 v22, 0, v22
	v_max_f32_e32 v30, 0, v30
	v_max_f32_e32 v6, 0, v6
	v_max_f32_e32 v14, 0, v14
	v_fmac_f32_e32 v18, v53, v21
	v_fmac_f32_e32 v26, v61, v29
	v_fmac_f32_e32 v2, v53, v5
	v_fmac_f32_e32 v10, v61, v13
	v_max_f32_e32 v23, 0, v23
	v_max_f32_e32 v31, 0, v31
	v_max_f32_e32 v7, 0, v7
	v_max_f32_e32 v15, 0, v15
	v_fmac_f32_e32 v18, v54, v22
	v_fmac_f32_e32 v26, v62, v30
	v_fmac_f32_e32 v2, v54, v6
	v_fmac_f32_e32 v10, v62, v14
	v_max_f32_e32 v24, 0, v24
	v_max_f32_e32 v32, 0, v32
	v_max_f32_e32 v8, 0, v8
	v_max_f32_e32 v16, 0, v16
	v_fmac_f32_e32 v18, v55, v23
	v_fmac_f32_e32 v26, v63, v31
	v_fmac_f32_e32 v2, v55, v7
	v_fmac_f32_e32 v10, v63, v15
	v_max_f32_e32 v25, 0, v25
	v_max_f32_e32 v33, 0, v33
	v_max_f32_e32 v9, 0, v9
	v_max_f32_e32 v17, 0, v17
	v_fmac_f32_e32 v18, v56, v24
	v_fmac_f32_e32 v26, v64, v32
	v_fmac_f32_e32 v2, v56, v8
	v_fmac_f32_e32 v10, v64, v16
	v_fmac_f32_e32 v18, v57, v25
	v_fmac_f32_e32 v26, v65, v33
	v_fmac_f32_e32 v2, v57, v9
	v_fmac_f32_e32 v10, v65, v17
	s_nop 1
	v_permlane32_swap_b32_e32 v18, v26
	v_permlane32_swap_b32_e32 v2, v10
	v_add_f32_e32 v3, v18, v26
	v_add_f32_e32 v2, v2, v10
	ds_write2_b32 v127, v3, v2 offset1:32
	v_add_u32_e32 v127, 0x100, v127
	s_cbranch_scc1 .LBB0_649
	s_mov_b32 s52, 0
	s_mov_b64 s[64:65], -1
	s_branch .LBB0_652
